# attention loop trimmed: dead m0 save/restore pairs and x+0 adds removed (10 issue slots per iteration)
# speedup vs baseline: 1.0046x; 1.0046x over previous
; #define WAIT_BAR(N) asm volatile("s_waitcnt vmcnt(" #N ") lgkmcnt(0)\n\ts_barrier":::"memory")
;   #define RESC() do{}while(0)
;   #define ROT() do{sl_prev=sl_cur;sl_cur=sl_next;sl_next=(sl_next==(NSLOT-1)*SLOTB)?0:sl_next+SLOTB;}while(0)
; template<int THRL> __device__ __forceinline__ void attn_unit(int b,int h,int qb,const bf16*Q,const bf16*__restrict__ K,const bf16*__restrict__ V,bf16*O,char*shm,float m2){
;     ...
;   int t=1;
;   for(;t+5<NT;t+=2){
;     STEP(pB0,pB1,pA0,pA1,t,true,true,true);     WAIT_BAR(2); RESC(); ROT();
.LBB0_829:
	v_add_u32_e32 v190, s17, v220
	ds_read_b64_tr_b16 v[230:231], v190 offset:24576
	ds_read_b64_tr_b16 v[232:233], v190 offset:25088
	s_waitcnt lgkmcnt(9)
	v_mfma_f32_32x32x16_bf16 v[114:129], v[98:101], v[174:177], v[50:65]
	v_exp_f32_e32 v78, v78
	v_add_f32_e32 v102, v82, v83
	v_add_f32_e32 v102, v84, v102
	v_add_f32_e32 v102, v85, v102
	v_add_f32_e32 v102, v86, v102
	v_add_f32_e32 v102, v87, v102
	v_cvt_pk_bf16_f32 v166, v82, v83
	v_cvt_pk_bf16_f32 v167, v84, v85
	ds_read_b64_tr_b16 v[82:83], v190 offset:28672
	ds_read_b64_tr_b16 v[84:85], v190 offset:29184
	v_add_f32_e32 v98, v88, v102
	v_add_f32_e32 v98, v89, v98
	v_add_f32_e32 v98, v90, v98
	v_add_f32_e32 v146, v91, v98
	s_waitcnt lgkmcnt(10)
	v_mfma_f32_32x32x16_bf16 v[98:113], v[182:185], v[174:177], v[50:65]
	v_exp_f32_e32 v79, v79
	v_cvt_pk_bf16_f32 v168, v86, v87
	v_cvt_pk_bf16_f32 v169, v88, v89
	ds_read_b64_tr_b16 v[86:87], v190 offset:25600
	ds_read_b64_tr_b16 v[88:89], v190 offset:26112
	v_add_f32_e32 v146, v92, v146
	v_add_f32_e32 v146, v93, v146
	v_add_f32_e32 v146, v94, v146
	v_add_f32_e32 v146, v95, v146
	v_cvt_pk_bf16_f32 v158, v90, v91
	v_cvt_pk_bf16_f32 v159, v92, v93
	s_waitcnt lgkmcnt(11)
	v_mfma_f32_32x32x16_bf16 v[114:129], v[186:189], v[170:173], v[114:129]
	v_exp_f32_e32 v80, v80
	ds_read_b64_tr_b16 v[90:91], v190 offset:29696
	ds_read_b64_tr_b16 v[92:93], v190 offset:30208
	s_waitcnt lgkmcnt(12)
	v_mfma_f32_32x32x16_bf16 v[98:113], v[178:181], v[170:173], v[98:113]
	v_exp_f32_e32 v81, v81
	v_add_f32_e32 v146, v96, v146
	v_add_f32_e32 v146, v97, v146
	v_add_f32_e32 v146, v66, v146
	v_add_f32_e32 v146, v67, v146
	v_cvt_pk_bf16_f32 v160, v94, v95
	v_cvt_pk_bf16_f32 v161, v96, v97
	ds_read_b64_tr_b16 v[94:95], v190 offset:26624
	ds_read_b64_tr_b16 v[96:97], v190 offset:27136
	s_waitcnt lgkmcnt(13)
	v_mfma_f32_32x32x16_bf16 v[114:129], v[142:145], v[162:165], v[114:129]
	v_add_f32_e32 v142, v68, v146
	v_add_f32_e32 v142, v69, v142
	v_add_f32_e32 v142, v70, v142
	v_add_f32_e32 v142, v71, v142
	v_cvt_pk_bf16_f32 v150, v66, v67
	v_cvt_pk_bf16_f32 v151, v68, v69
	ds_read_b64_tr_b16 v[66:67], v190 offset:30720
	ds_read_b64_tr_b16 v[68:69], v190 offset:31232
	s_waitcnt lgkmcnt(14)
	v_mfma_f32_32x32x16_bf16 v[98:113], v[138:141], v[162:165], v[98:113]
	v_add_f32_e32 v138, v72, v142
	v_add_f32_e32 v138, v73, v138
	v_add_f32_e32 v138, v74, v138
	v_add_f32_e32 v138, v75, v138
	v_cvt_pk_bf16_f32 v152, v70, v71
	v_cvt_pk_bf16_f32 v153, v72, v73
	ds_read_b64_tr_b16 v[70:71], v190 offset:27648
	ds_read_b64_tr_b16 v[72:73], v190 offset:28160
	s_waitcnt lgkmcnt(14)
	v_mfma_f32_32x32x16_bf16 v[114:129], v[134:137], v[154:157], v[114:129]
	v_add_f32_e32 v134, v76, v138
	v_add_f32_e32 v134, v77, v134
	v_add_f32_e32 v134, v78, v134
	v_add_f32_e32 v134, v79, v134
	v_cvt_pk_bf16_f32 v146, v74, v75
	v_cvt_pk_bf16_f32 v147, v76, v77
	ds_read_b64_tr_b16 v[74:75], v190 offset:31744
	ds_read_b64_tr_b16 v[76:77], v190 offset:32256
	v_mfma_f32_32x32x16_bf16 v[98:113], v[130:133], v[154:157], v[98:113]
	v_add_f32_e32 v130, v80, v134
	v_add_f32_e32 v130, v81, v130
	v_cvt_pk_bf16_f32 v148, v78, v79
	v_cvt_pk_bf16_f32 v149, v80, v81
	v_lshl_add_u64 v[78:79], v[214:215], 0, s[48:49]
	s_add_i32 s0, s16, s12
	s_mov_b32 m0, s0
	s_nop 0
	global_load_lds_dwordx4 v[78:79], off
	v_lshl_add_u64 v[78:79], v[216:217], 0, s[42:43]
	s_add_i32 s0, s15, s4
	s_mov_b32 m0, s0
	s_nop 0
	global_load_lds_dwordx4 v[78:79], off
	v_add_f32_e32 v190, v199, v130
	s_waitcnt lgkmcnt(14)
	v_mfma_f32_32x32x16_bf16 v[18:33], v[166:169], v[230:233], v[18:33]
	v_exp_f32_e32 v114, v114
	v_exp_f32_e32 v115, v115
	v_exp_f32_e32 v116, v116
	v_exp_f32_e32 v117, v117
	s_waitcnt lgkmcnt(12)
	v_mfma_f32_32x32x16_bf16 v[34:49], v[166:169], v[82:85], v[34:49]
	v_exp_f32_e32 v118, v118
	v_exp_f32_e32 v119, v119
	v_exp_f32_e32 v120, v120
	v_exp_f32_e32 v121, v121
	v_add_u32_e32 v82, s15, v219
	ds_read_b128 v[78:81], v82
	ds_read_b128 v[134:137], v82 offset:512
	s_waitcnt lgkmcnt(12)
	v_mfma_f32_32x32x16_bf16 v[18:33], v[158:161], v[86:89], v[18:33]
	v_exp_f32_e32 v122, v122
	v_exp_f32_e32 v123, v123
	v_exp_f32_e32 v124, v124
	v_exp_f32_e32 v125, v125
	ds_read_b128 v[138:141], v82 offset:2048
	ds_read_b128 v[142:145], v82 offset:2560
	s_waitcnt lgkmcnt(12)
	v_mfma_f32_32x32x16_bf16 v[34:49], v[158:161], v[90:93], v[34:49]
	v_exp_f32_e32 v126, v126
	v_exp_f32_e32 v127, v127
	v_exp_f32_e32 v128, v128
	v_exp_f32_e32 v129, v129
	ds_read_b128 v[178:181], v82 offset:4096
	ds_read_b128 v[182:185], v82 offset:4608
	s_waitcnt lgkmcnt(12)
	v_mfma_f32_32x32x16_bf16 v[18:33], v[150:153], v[94:97], v[18:33]
	v_exp_f32_e32 v98, v98
	v_exp_f32_e32 v99, v99
	v_exp_f32_e32 v100, v100
	v_exp_f32_e32 v101, v101
	ds_read_b128 v[186:189], v82 offset:6144
	ds_read_b128 v[130:133], v82 offset:6656
	s_waitcnt lgkmcnt(12)
	v_mfma_f32_32x32x16_bf16 v[34:49], v[150:153], v[66:69], v[34:49]
	v_exp_f32_e32 v102, v102
	v_exp_f32_e32 v103, v103
	v_exp_f32_e32 v104, v104
	v_exp_f32_e32 v105, v105
	s_waitcnt lgkmcnt(10)
	v_mfma_f32_32x32x16_bf16 v[18:33], v[146:149], v[70:73], v[18:33]
	v_exp_f32_e32 v106, v106
	v_exp_f32_e32 v107, v107
	v_exp_f32_e32 v108, v108
	v_exp_f32_e32 v109, v109
	s_waitcnt lgkmcnt(8)
	v_mfma_f32_32x32x16_bf16 v[34:49], v[146:149], v[74:77], v[34:49]
	s_waitcnt vmcnt(2) lgkmcnt(0)
	s_barrier
; #define WAIT_BAR(N) asm volatile("s_waitcnt vmcnt(" #N ") lgkmcnt(0)\n\ts_barrier":::"memory")
;   #define RESC() do{}while(0)
;   #define ROT() do{sl_prev=sl_cur;sl_cur=sl_next;sl_next=(sl_next==(NSLOT-1)*SLOTB)?0:sl_next+SLOTB;}while(0)
; template<int THRL> __device__ __forceinline__ void attn_unit(int b,int h,int qb,const bf16*Q,const bf16*__restrict__ K,const bf16*__restrict__ V,bf16*O,char*shm,float m2){
;     ...
;   int t=1;
;   for(;t+5<NT;t+=2){
;     STEP(pB0,pB1,pA0,pA1,t,true,true,true);     WAIT_BAR(2); RESC(); ROT();
;     STEP(pA0,pA1,pB0,pB1,t+1,true,true,true);   WAIT_BAR(2); RESC(); ROT();
	s_add_i32 s0, s15, 0x2000
	s_cmpk_lg_i32 s15, 0x4000
	s_cselect_b32 s0, s0, 0
	v_add_u32_e32 v199, s16, v220
	ds_read_b64_tr_b16 v[230:231], v199 offset:24576
	ds_read_b64_tr_b16 v[232:233], v199 offset:25088
	s_waitcnt lgkmcnt(9)
	v_mfma_f32_32x32x16_bf16 v[82:97], v[78:81], v[174:177], v[50:65]
	v_exp_f32_e32 v110, v110
	v_add_f32_e32 v66, v114, v115
	v_add_f32_e32 v66, v116, v66
	v_add_f32_e32 v66, v117, v66
	v_add_f32_e32 v66, v118, v66
	v_add_f32_e32 v66, v119, v66
	v_cvt_pk_bf16_f32 v166, v114, v115
	v_cvt_pk_bf16_f32 v167, v116, v117
	ds_read_b64_tr_b16 v[114:115], v199 offset:28672
	ds_read_b64_tr_b16 v[116:117], v199 offset:29184
	v_add_f32_e32 v66, v120, v66
	v_add_f32_e32 v66, v121, v66
	v_add_f32_e32 v66, v122, v66
	v_add_f32_e32 v146, v123, v66
	s_waitcnt lgkmcnt(10)
	v_mfma_f32_32x32x16_bf16 v[66:81], v[134:137], v[174:177], v[50:65]
	v_exp_f32_e32 v111, v111
	v_cvt_pk_bf16_f32 v168, v118, v119
	v_cvt_pk_bf16_f32 v169, v120, v121
	ds_read_b64_tr_b16 v[118:119], v199 offset:25600
	ds_read_b64_tr_b16 v[120:121], v199 offset:26112
	s_waitcnt lgkmcnt(11)
	v_mfma_f32_32x32x16_bf16 v[82:97], v[138:141], v[170:173], v[82:97]
	v_exp_f32_e32 v112, v112
	v_add_f32_e32 v134, v124, v146
	v_add_f32_e32 v134, v125, v134
	v_add_f32_e32 v134, v126, v134
	v_add_f32_e32 v134, v127, v134
	v_cvt_pk_bf16_f32 v158, v122, v123
	v_cvt_pk_bf16_f32 v159, v124, v125
	ds_read_b64_tr_b16 v[122:123], v199 offset:29696
	ds_read_b64_tr_b16 v[124:125], v199 offset:30208
	s_waitcnt lgkmcnt(12)
	v_mfma_f32_32x32x16_bf16 v[66:81], v[142:145], v[170:173], v[66:81]
	v_exp_f32_e32 v113, v113
	v_add_f32_e32 v134, v128, v134
	v_add_f32_e32 v134, v129, v134
	v_add_f32_e32 v134, v98, v134
	v_add_f32_e32 v134, v99, v134
	v_cvt_pk_bf16_f32 v160, v126, v127
	v_cvt_pk_bf16_f32 v161, v128, v129
	ds_read_b64_tr_b16 v[126:127], v199 offset:26624
	ds_read_b64_tr_b16 v[128:129], v199 offset:27136
	s_waitcnt lgkmcnt(13)
	v_mfma_f32_32x32x16_bf16 v[82:97], v[178:181], v[162:165], v[82:97]
	v_add_f32_e32 v134, v100, v134
	v_add_f32_e32 v134, v101, v134
	v_add_f32_e32 v134, v102, v134
	v_add_f32_e32 v134, v103, v134
	v_cvt_pk_bf16_f32 v150, v98, v99
	v_cvt_pk_bf16_f32 v151, v100, v101
	ds_read_b64_tr_b16 v[234:235], v199 offset:30720
	ds_read_b64_tr_b16 v[236:237], v199 offset:31232
	s_waitcnt lgkmcnt(14)
	v_mfma_f32_32x32x16_bf16 v[66:81], v[182:185], v[162:165], v[66:81]
	v_add_f32_e32 v98, v104, v134
	v_add_f32_e32 v98, v105, v98
	v_add_f32_e32 v98, v106, v98
	v_add_f32_e32 v98, v107, v98
	v_cvt_pk_bf16_f32 v152, v102, v103
	v_cvt_pk_bf16_f32 v153, v104, v105
	ds_read_b64_tr_b16 v[102:103], v199 offset:27648
	ds_read_b64_tr_b16 v[104:105], v199 offset:28160
	s_waitcnt lgkmcnt(14)
	v_mfma_f32_32x32x16_bf16 v[82:97], v[186:189], v[154:157], v[82:97]
	v_add_f32_e32 v98, v108, v98
	v_add_f32_e32 v98, v109, v98
	v_add_f32_e32 v98, v110, v98
	v_add_f32_e32 v98, v111, v98
	v_cvt_pk_bf16_f32 v146, v106, v107
	v_cvt_pk_bf16_f32 v147, v108, v109
	ds_read_b64_tr_b16 v[106:107], v199 offset:31744
	ds_read_b64_tr_b16 v[108:109], v199 offset:32256
	v_mfma_f32_32x32x16_bf16 v[66:81], v[130:133], v[154:157], v[66:81]
	v_add_f32_e32 v98, v112, v98
	v_add_f32_e32 v98, v113, v98
	v_cvt_pk_bf16_f32 v148, v110, v111
	v_cvt_pk_bf16_f32 v149, v112, v113
	s_mov_b64 s[16:17], 0x10000
	v_add_f32_e32 v199, v190, v98
	v_lshl_add_u64 v[98:99], v[214:215], 0, s[16:17]
	s_add_i32 s16, s15, s12
	s_mov_b32 m0, s16
	s_nop 0
	global_load_lds_dwordx4 v[98:99], off
	v_lshl_add_u64 v[216:217], v[216:217], 0, s[46:47]
	s_add_i32 s16, s0, s4
	s_mov_b32 m0, s16
	s_nop 0
	global_load_lds_dwordx4 v[216:217], off
	s_waitcnt lgkmcnt(14)
	v_mfma_f32_32x32x16_bf16 v[18:33], v[166:169], v[230:233], v[18:33]
	v_exp_f32_e32 v82, v82
	v_exp_f32_e32 v83, v83
	v_exp_f32_e32 v84, v84
	v_exp_f32_e32 v85, v85
	s_waitcnt lgkmcnt(12)
	v_mfma_f32_32x32x16_bf16 v[34:49], v[166:169], v[114:117], v[34:49]
	v_exp_f32_e32 v86, v86
	v_exp_f32_e32 v87, v87
	v_exp_f32_e32 v88, v88
	v_exp_f32_e32 v89, v89
	v_add_u32_e32 v110, s0, v219
	ds_read_b128 v[98:101], v110
	ds_read_b128 v[182:185], v110 offset:512
	s_waitcnt lgkmcnt(12)
	v_mfma_f32_32x32x16_bf16 v[18:33], v[158:161], v[118:121], v[18:33]
	v_exp_f32_e32 v90, v90
	v_exp_f32_e32 v91, v91
	v_exp_f32_e32 v92, v92
	v_exp_f32_e32 v93, v93
	ds_read_b128 v[186:189], v110 offset:2048
	ds_read_b128 v[178:181], v110 offset:2560
	s_waitcnt lgkmcnt(12)
	v_mfma_f32_32x32x16_bf16 v[34:49], v[158:161], v[122:125], v[34:49]
	v_exp_f32_e32 v94, v94
	v_exp_f32_e32 v95, v95
	v_exp_f32_e32 v96, v96
	v_exp_f32_e32 v97, v97
	ds_read_b128 v[142:145], v110 offset:4096
	ds_read_b128 v[138:141], v110 offset:4608
	s_waitcnt lgkmcnt(12)
	v_mfma_f32_32x32x16_bf16 v[18:33], v[150:153], v[126:129], v[18:33]
	v_exp_f32_e32 v66, v66
	v_exp_f32_e32 v67, v67
	v_exp_f32_e32 v68, v68
	v_exp_f32_e32 v69, v69
	ds_read_b128 v[134:137], v110 offset:6144
	ds_read_b128 v[130:133], v110 offset:6656
	s_waitcnt lgkmcnt(12)
	v_mfma_f32_32x32x16_bf16 v[34:49], v[150:153], v[234:237], v[34:49]
	v_exp_f32_e32 v70, v70
	v_exp_f32_e32 v71, v71
	v_exp_f32_e32 v72, v72
	v_exp_f32_e32 v73, v73
	s_waitcnt lgkmcnt(10)
	v_mfma_f32_32x32x16_bf16 v[18:33], v[146:149], v[102:105], v[18:33]
	v_exp_f32_e32 v74, v74
	v_exp_f32_e32 v75, v75
	v_exp_f32_e32 v76, v76
	v_exp_f32_e32 v77, v77
	s_waitcnt lgkmcnt(8)
	v_mfma_f32_32x32x16_bf16 v[34:49], v[146:149], v[106:109], v[34:49]
	s_add_i32 s18, s0, 0x2000
	s_waitcnt vmcnt(2) lgkmcnt(0)
	s_barrier
	s_cmpk_lg_i32 s0, 0x4000
	s_mov_b32 s17, s15
	s_cselect_b32 s15, s18, 0
	s_add_i32 s14, s14, 2
	v_lshl_add_u64 v[214:215], v[214:215], 0, s[46:47]
	s_mov_b32 s16, s0
	s_cmpk_gt_u32 s14, 0x78
	s_cbranch_scc0 .LBB0_829
; #define WAIT_BAR(N) asm volatile("s_waitcnt vmcnt(" #N ") lgkmcnt(0)\n\ts_barrier":::"memory")
;   #define RESC() do{}while(0)
;   #define ROT() do{sl_prev=sl_cur;sl_cur=sl_next;sl_next=(sl_next==(NSLOT-1)*SLOTB)?0:sl_next+SLOTB;}while(0)
;   #define ENDW(tt) do{ if((tt)+3<NT){WAIT_BAR(2);} else if((tt)+2<NT){WAIT_BAR(1);} else {WAIT_BAR(0);} }while(0)
; template<int THRL> __device__ __forceinline__ void attn_unit(int b,int h,int qb,const bf16*Q,const bf16*__restrict__ K,const bf16*__restrict__ V,bf16*O,char*shm,float m2){
;     ...
;   int t=1;
;   for(;t+5<NT;t+=2){
;     STEP(pB0,pB1,pA0,pA1,t,true,true,true);     WAIT_BAR(2); RESC(); ROT();
;     STEP(pA0,pA1,pB0,pB1,t+1,true,true,true);   WAIT_BAR(2); RESC(); ROT();
;   }
;     ...
;   for(;t+1<NT;t+=2){
;     STEP(pB0,pB1,pA0,pA1,t,(t+3<NT),(t+1<NT),(t+1<NT));       ENDW(t);   RESC(); ROT();
;     STEP(pA0,pA1,pB0,pB1,t+1,(t+4<NT),(t+2<NT),(t+2<NT));     ENDW(t+1); RESC(); ROT();
	v_exp_f32_e32 v78, v78
	v_exp_f32_e32 v79, v79
	v_exp_f32_e32 v80, v80
	v_exp_f32_e32 v81, v81
	s_and_b32 s0, s13, 0x3fffffc0
	s_lshl_b32 s0, s0, 2
	s_add_i32 s0, s0, 0
	ds_read_b64_tr_b16 v[214:215], v220 offset:40960
	ds_read_b64_tr_b16 v[216:217], v220 offset:41472
	v_add_f32_e32 v102, v82, v83
	v_add_f32_e32 v102, v84, v102
	v_add_f32_e32 v102, v85, v102
	v_add_f32_e32 v102, v86, v102
	v_add_f32_e32 v102, v87, v102
	v_cvt_pk_bf16_f32 v166, v82, v83
	v_cvt_pk_bf16_f32 v167, v84, v85
	s_waitcnt lgkmcnt(9)
	v_mfma_f32_32x32x16_bf16 v[114:129], v[98:101], v[174:177], v[50:65]
	ds_read_b64_tr_b16 v[82:83], v220 offset:45056
	ds_read_b64_tr_b16 v[84:85], v220 offset:45568
	v_add_f32_e32 v98, v88, v102
	v_add_f32_e32 v98, v89, v98
	v_add_f32_e32 v98, v90, v98
	v_add_f32_e32 v146, v91, v98
	v_cvt_pk_bf16_f32 v168, v86, v87
	v_cvt_pk_bf16_f32 v169, v88, v89
	s_waitcnt lgkmcnt(10)
	v_mfma_f32_32x32x16_bf16 v[98:113], v[182:185], v[174:177], v[50:65]
	ds_read_b64_tr_b16 v[86:87], v220 offset:41984
	ds_read_b64_tr_b16 v[88:89], v220 offset:42496
	v_add_f32_e32 v146, v92, v146
	v_add_f32_e32 v146, v93, v146
	v_add_f32_e32 v146, v94, v146
	v_add_f32_e32 v146, v95, v146
	v_cvt_pk_bf16_f32 v158, v90, v91
	v_cvt_pk_bf16_f32 v159, v92, v93
	s_waitcnt lgkmcnt(11)
	v_mfma_f32_32x32x16_bf16 v[114:129], v[186:189], v[170:173], v[114:129]
	ds_read_b64_tr_b16 v[90:91], v220 offset:46080
	ds_read_b64_tr_b16 v[92:93], v220 offset:46592
	v_add_f32_e32 v146, v96, v146
	v_add_f32_e32 v146, v97, v146
	v_add_f32_e32 v146, v66, v146
	v_add_f32_e32 v146, v67, v146
	v_cvt_pk_bf16_f32 v160, v94, v95
	v_cvt_pk_bf16_f32 v161, v96, v97
	s_waitcnt lgkmcnt(12)
	v_mfma_f32_32x32x16_bf16 v[98:113], v[178:181], v[170:173], v[98:113]
	ds_read_b64_tr_b16 v[94:95], v220 offset:43008
	ds_read_b64_tr_b16 v[96:97], v220 offset:43520
	s_waitcnt lgkmcnt(13)
	v_mfma_f32_32x32x16_bf16 v[114:129], v[142:145], v[162:165], v[114:129]
	v_add_f32_e32 v142, v68, v146
	v_add_f32_e32 v142, v69, v142
	v_add_f32_e32 v142, v70, v142
	v_add_f32_e32 v142, v71, v142
	v_cvt_pk_bf16_f32 v150, v66, v67
	v_cvt_pk_bf16_f32 v151, v68, v69
	ds_read_b64_tr_b16 v[66:67], v220 offset:47104
	ds_read_b64_tr_b16 v[68:69], v220 offset:47616
	s_waitcnt lgkmcnt(14)
	v_mfma_f32_32x32x16_bf16 v[98:113], v[138:141], v[162:165], v[98:113]
	v_add_f32_e32 v138, v72, v142
	v_add_f32_e32 v138, v73, v138
	v_add_f32_e32 v138, v74, v138
	v_add_f32_e32 v138, v75, v138
	v_cvt_pk_bf16_f32 v152, v70, v71
	v_cvt_pk_bf16_f32 v153, v72, v73
	ds_read_b64_tr_b16 v[70:71], v220 offset:44032
	ds_read_b64_tr_b16 v[72:73], v220 offset:44544
	s_waitcnt lgkmcnt(14)
	v_mfma_f32_32x32x16_bf16 v[114:129], v[134:137], v[154:157], v[114:129]
	v_add_f32_e32 v134, v76, v138
	v_add_f32_e32 v134, v77, v134
	v_add_f32_e32 v134, v78, v134
	v_add_f32_e32 v134, v79, v134
	v_cvt_pk_bf16_f32 v146, v74, v75
	v_cvt_pk_bf16_f32 v147, v76, v77
	ds_read_b64_tr_b16 v[74:75], v220 offset:48128
	ds_read_b64_tr_b16 v[76:77], v220 offset:48640
	v_mfma_f32_32x32x16_bf16 v[98:113], v[130:133], v[154:157], v[98:113]
	v_add_f32_e32 v130, v80, v134
	v_add_f32_e32 v130, v81, v130
	v_add_f32_e32 v130, 0, v130
	v_cvt_pk_bf16_f32 v148, v78, v79
	v_cvt_pk_bf16_f32 v149, v80, v81
	v_lshl_add_u64 v[78:79], v[212:213], 0, s[50:51]
	s_mov_b32 s13, m0
	s_mov_b32 m0, s12
	s_nop 0
	global_load_lds_dwordx4 v[78:79], off
	s_mov_b32 m0, s13
	s_mov_b64 s[12:13], 0x1f0000
	s_cmp_lg_u32 0, -1
	v_lshl_add_u64 v[78:79], v[210:211], 0, s[12:13]
	s_cselect_b32 s12, 0, 0
	s_add_i32 s12, s12, s5
	s_add_i32 s5, s12, 0x8000
	s_mov_b32 s13, m0
	s_mov_b32 m0, s5
	s_nop 0
	global_load_lds_dwordx4 v[78:79], off
	s_mov_b32 m0, s13
	v_add_f32_e32 v190, v199, v130
	s_waitcnt lgkmcnt(14)
	v_mfma_f32_32x32x16_bf16 v[18:33], v[166:169], v[214:217], v[18:33]
	v_exp_f32_e32 v114, v114
	v_exp_f32_e32 v115, v115
	v_exp_f32_e32 v116, v116
	v_exp_f32_e32 v117, v117
	s_waitcnt lgkmcnt(12)
	v_mfma_f32_32x32x16_bf16 v[34:49], v[166:169], v[82:85], v[34:49]
	v_exp_f32_e32 v118, v118
	v_exp_f32_e32 v119, v119
	v_exp_f32_e32 v120, v120
	v_exp_f32_e32 v121, v121
	ds_read_b128 v[78:81], v219 offset:8192
	ds_read_b128 v[178:181], v219 offset:8704
	s_waitcnt lgkmcnt(12)
	v_mfma_f32_32x32x16_bf16 v[18:33], v[158:161], v[86:89], v[18:33]
	v_exp_f32_e32 v122, v122
	v_exp_f32_e32 v123, v123
	v_exp_f32_e32 v124, v124
	v_exp_f32_e32 v125, v125
	ds_read_b128 v[86:89], v219 offset:10240
	ds_read_b128 v[182:185], v219 offset:10752
	s_waitcnt lgkmcnt(12)
	v_mfma_f32_32x32x16_bf16 v[34:49], v[158:161], v[90:93], v[34:49]
	v_exp_f32_e32 v126, v126
	v_exp_f32_e32 v127, v127
	v_exp_f32_e32 v128, v128
	v_exp_f32_e32 v129, v129
	ds_read_b128 v[90:93], v219 offset:12288
	ds_read_b128 v[186:189], v219 offset:12800
	s_waitcnt lgkmcnt(12)
	v_mfma_f32_32x32x16_bf16 v[18:33], v[150:153], v[94:97], v[18:33]
	v_exp_f32_e32 v98, v98
	v_exp_f32_e32 v99, v99
	v_exp_f32_e32 v100, v100
	v_exp_f32_e32 v101, v101
	ds_read_b128 v[94:97], v219 offset:14336
	ds_read_b128 v[82:85], v219 offset:14848
	s_waitcnt lgkmcnt(12)
	v_mfma_f32_32x32x16_bf16 v[34:49], v[150:153], v[66:69], v[34:49]
	v_exp_f32_e32 v102, v102
	v_exp_f32_e32 v103, v103
	v_exp_f32_e32 v104, v104
	v_exp_f32_e32 v105, v105
	s_waitcnt lgkmcnt(10)
	v_mfma_f32_32x32x16_bf16 v[18:33], v[146:149], v[70:73], v[18:33]
	v_exp_f32_e32 v106, v106
	v_exp_f32_e32 v107, v107
	v_exp_f32_e32 v108, v108
	v_exp_f32_e32 v109, v109
	s_waitcnt lgkmcnt(8)
	v_mfma_f32_32x32x16_bf16 v[34:49], v[146:149], v[74:77], v[34:49]
	v_exp_f32_e32 v110, v110
	v_exp_f32_e32 v111, v111
	v_exp_f32_e32 v112, v112
	v_exp_f32_e32 v113, v113
	s_waitcnt vmcnt(2) lgkmcnt(0)
	s_barrier
; #define WAIT_BAR(N) asm volatile("s_waitcnt vmcnt(" #N ") lgkmcnt(0)\n\ts_barrier":::"memory")
;   #define RESC() do{}while(0)
;   #define ROT() do{sl_prev=sl_cur;sl_cur=sl_next;sl_next=(sl_next==(NSLOT-1)*SLOTB)?0:sl_next+SLOTB;}while(0)
;   #define ENDW(tt) do{ if((tt)+3<NT){WAIT_BAR(2);} else if((tt)+2<NT){WAIT_BAR(1);} else {WAIT_BAR(0);} }while(0)
; template<int THRL> __device__ __forceinline__ void attn_unit(int b,int h,int qb,const bf16*Q,const bf16*__restrict__ K,const bf16*__restrict__ V,bf16*O,char*shm,float m2){
;     ...
;   int t=1;
;   for(;t+5<NT;t+=2){
;     STEP(pB0,pB1,pA0,pA1,t,true,true,true);     WAIT_BAR(2); RESC(); ROT();
;     STEP(pA0,pA1,pB0,pB1,t+1,true,true,true);   WAIT_BAR(2); RESC(); ROT();
;   }
;     ...
;   for(;t+1<NT;t+=2){
;     STEP(pB0,pB1,pA0,pA1,t,(t+3<NT),(t+1<NT),(t+1<NT));       ENDW(t);   RESC(); ROT();
;     STEP(pA0,pA1,pB0,pB1,t+1,(t+4<NT),(t+2<NT),(t+2<NT));     ENDW(t+1); RESC(); ROT();
	ds_read_b64_tr_b16 v[214:215], v220 offset:24576
	ds_read_b64_tr_b16 v[216:217], v220 offset:25088
	v_add_f32_e32 v66, v114, v115
	v_add_f32_e32 v66, v116, v66
	v_add_f32_e32 v66, v117, v66
	v_add_f32_e32 v66, v118, v66
	v_add_f32_e32 v66, v119, v66
	v_cvt_pk_bf16_f32 v166, v114, v115
	v_cvt_pk_bf16_f32 v167, v116, v117
	s_waitcnt lgkmcnt(9)
	v_mfma_f32_32x32x16_bf16 v[130:145], v[78:81], v[174:177], v[50:65]
	ds_read_b64_tr_b16 v[114:115], v220 offset:28672
	ds_read_b64_tr_b16 v[116:117], v220 offset:29184
	v_add_f32_e32 v66, v120, v66
	v_add_f32_e32 v66, v121, v66
	v_add_f32_e32 v66, v122, v66
	v_add_f32_e32 v146, v123, v66
	s_waitcnt lgkmcnt(10)
	v_mfma_f32_32x32x16_bf16 v[66:81], v[178:181], v[174:177], v[50:65]
	v_cvt_pk_bf16_f32 v168, v118, v119
	v_cvt_pk_bf16_f32 v169, v120, v121
	ds_read_b64_tr_b16 v[118:119], v220 offset:25600
	ds_read_b64_tr_b16 v[120:121], v220 offset:26112
	s_waitcnt lgkmcnt(11)
	v_mfma_f32_32x32x16_bf16 v[130:145], v[86:89], v[170:173], v[130:145]
	v_add_f32_e32 v86, v124, v146
	v_add_f32_e32 v86, v125, v86
	v_add_f32_e32 v86, v126, v86
	v_add_f32_e32 v146, v127, v86
	v_cvt_pk_bf16_f32 v158, v122, v123
	v_cvt_pk_bf16_f32 v159, v124, v125
	ds_read_b64_tr_b16 v[86:87], v220 offset:29696
	ds_read_b64_tr_b16 v[88:89], v220 offset:30208
	s_waitcnt lgkmcnt(12)
	v_mfma_f32_32x32x16_bf16 v[66:81], v[182:185], v[170:173], v[66:81]
	v_add_f32_e32 v122, v128, v146
	v_add_f32_e32 v122, v129, v122
	v_add_f32_e32 v122, v98, v122
	v_add_f32_e32 v146, v99, v122
	v_cvt_pk_bf16_f32 v160, v126, v127
	v_cvt_pk_bf16_f32 v161, v128, v129
	ds_read_b64_tr_b16 v[122:123], v220 offset:26624
	ds_read_b64_tr_b16 v[124:125], v220 offset:27136
	s_waitcnt lgkmcnt(13)
	v_mfma_f32_32x32x16_bf16 v[130:145], v[90:93], v[162:165], v[130:145]
	v_add_f32_e32 v90, v100, v146
	v_add_f32_e32 v90, v101, v90
	v_add_f32_e32 v90, v102, v90
	v_add_f32_e32 v126, v103, v90
	v_cvt_pk_bf16_f32 v150, v98, v99
	v_cvt_pk_bf16_f32 v151, v100, v101
	ds_read_b64_tr_b16 v[90:91], v220 offset:30720
	ds_read_b64_tr_b16 v[92:93], v220 offset:31232
	s_waitcnt lgkmcnt(14)
	v_mfma_f32_32x32x16_bf16 v[66:81], v[186:189], v[162:165], v[66:81]
	v_add_f32_e32 v98, v104, v126
	v_add_f32_e32 v98, v105, v98
	v_add_f32_e32 v98, v106, v98
	v_add_f32_e32 v98, v107, v98
	v_cvt_pk_bf16_f32 v152, v102, v103
	v_cvt_pk_bf16_f32 v153, v104, v105
	ds_read_b64_tr_b16 v[102:103], v220 offset:27648
	ds_read_b64_tr_b16 v[104:105], v220 offset:28160
	s_waitcnt lgkmcnt(14)
	v_mfma_f32_32x32x16_bf16 v[130:145], v[94:97], v[154:157], v[130:145]
	v_add_f32_e32 v94, v108, v98
	v_add_f32_e32 v94, v109, v94
	v_add_f32_e32 v94, v110, v94
	v_add_f32_e32 v98, v111, v94
	v_cvt_pk_bf16_f32 v146, v106, v107
	v_cvt_pk_bf16_f32 v147, v108, v109
	ds_read_b64_tr_b16 v[94:95], v220 offset:31744
	ds_read_b64_tr_b16 v[96:97], v220 offset:32256
	v_mfma_f32_32x32x16_bf16 v[66:81], v[82:85], v[154:157], v[66:81]
	v_add_f32_e32 v82, v112, v98
	v_add_f32_e32 v82, v113, v82
	v_add_f32_e32 v82, 0, v82
	v_cvt_pk_bf16_f32 v148, v110, v111
	v_cvt_pk_bf16_f32 v149, v112, v113
	s_nop 0
	v_add_f32_e32 v190, v190, v82
	v_lshl_add_u64 v[82:83], v[212:213], 0, s[52:53]
	s_add_i32 s13, s12, 0x2000
	s_mov_b32 s14, m0
	s_mov_b32 m0, s13
	s_nop 0
	global_load_lds_dwordx4 v[82:83], off
	s_mov_b32 m0, s14
	s_mov_b64 s[14:15], 0x1f4000
	v_lshl_add_u64 v[82:83], v[210:211], 0, s[14:15]
	s_add_i32 s12, s12, 0xa000
	s_mov_b32 s13, m0
	s_mov_b32 m0, s12
	s_nop 0
	global_load_lds_dwordx4 v[82:83], off
	s_mov_b32 m0, s13
	s_waitcnt lgkmcnt(14)
	v_mfma_f32_32x32x16_bf16 v[18:33], v[166:169], v[214:217], v[18:33]
	v_exp_f32_e32 v130, v130
	v_exp_f32_e32 v131, v131
	v_exp_f32_e32 v132, v132
	v_exp_f32_e32 v133, v133
	s_waitcnt lgkmcnt(12)
	v_mfma_f32_32x32x16_bf16 v[34:49], v[166:169], v[114:117], v[34:49]
	v_exp_f32_e32 v134, v134
	v_exp_f32_e32 v135, v135
	v_exp_f32_e32 v136, v136
	v_exp_f32_e32 v137, v137
	ds_read_b128 v[82:85], v219 offset:16384
	ds_read_b128 v[106:109], v219 offset:16896
	s_waitcnt lgkmcnt(12)
	v_mfma_f32_32x32x16_bf16 v[18:33], v[158:161], v[118:121], v[18:33]
	v_exp_f32_e32 v138, v138
	v_exp_f32_e32 v139, v139
	v_exp_f32_e32 v140, v140
	v_exp_f32_e32 v141, v141
	ds_read_b128 v[110:113], v219 offset:18432
	ds_read_b128 v[178:181], v219 offset:18944
	s_waitcnt lgkmcnt(12)
	v_mfma_f32_32x32x16_bf16 v[34:49], v[158:161], v[86:89], v[34:49]
	v_exp_f32_e32 v142, v142
	v_exp_f32_e32 v143, v143
	v_exp_f32_e32 v144, v144
	v_exp_f32_e32 v145, v145
	ds_read_b128 v[182:185], v219 offset:20480
	ds_read_b128 v[186:189], v219 offset:20992
	s_waitcnt lgkmcnt(12)
	v_mfma_f32_32x32x16_bf16 v[18:33], v[150:153], v[122:125], v[18:33]
	v_exp_f32_e32 v66, v66
	v_exp_f32_e32 v67, v67
	v_exp_f32_e32 v68, v68
	v_exp_f32_e32 v69, v69
	ds_read_b128 v[212:215], v219 offset:22528
	ds_read_b128 v[98:101], v219 offset:23040
	s_waitcnt lgkmcnt(12)
	v_mfma_f32_32x32x16_bf16 v[34:49], v[150:153], v[90:93], v[34:49]
	v_exp_f32_e32 v70, v70
	v_exp_f32_e32 v71, v71
	v_exp_f32_e32 v72, v72
	v_exp_f32_e32 v73, v73
	s_waitcnt lgkmcnt(10)
	v_mfma_f32_32x32x16_bf16 v[18:33], v[146:149], v[102:105], v[18:33]
	v_exp_f32_e32 v74, v74
	v_exp_f32_e32 v75, v75
	v_exp_f32_e32 v76, v76
	v_exp_f32_e32 v77, v77
	s_waitcnt lgkmcnt(8)
	v_mfma_f32_32x32x16_bf16 v[34:49], v[146:149], v[94:97], v[34:49]
	v_exp_f32_e32 v78, v78
	v_exp_f32_e32 v79, v79
	v_exp_f32_e32 v80, v80
	v_exp_f32_e32 v81, v81
	s_waitcnt vmcnt(2) lgkmcnt(0)
	s_barrier
; #define WAIT_BAR(N) asm volatile("s_waitcnt vmcnt(" #N ") lgkmcnt(0)\n\ts_barrier":::"memory")
;   #define RESC() do{}while(0)
;   #define ROT() do{sl_prev=sl_cur;sl_cur=sl_next;sl_next=(sl_next==(NSLOT-1)*SLOTB)?0:sl_next+SLOTB;}while(0)
;   #define ENDW(tt) do{ if((tt)+3<NT){WAIT_BAR(2);} else if((tt)+2<NT){WAIT_BAR(1);} else {WAIT_BAR(0);} }while(0)
; template<int THRL> __device__ __forceinline__ void attn_unit(int b,int h,int qb,const bf16*Q,const bf16*__restrict__ K,const bf16*__restrict__ V,bf16*O,char*shm,float m2){
;     ...
;   int t=1;
;   for(;t+5<NT;t+=2){
;     STEP(pB0,pB1,pA0,pA1,t,true,true,true);     WAIT_BAR(2); RESC(); ROT();
;     STEP(pA0,pA1,pB0,pB1,t+1,true,true,true);   WAIT_BAR(2); RESC(); ROT();
;   }
;     ...
;   for(;t+1<NT;t+=2){
;     STEP(pB0,pB1,pA0,pA1,t,(t+3<NT),(t+1<NT),(t+1<NT));       ENDW(t);   RESC(); ROT();
;     STEP(pA0,pA1,pB0,pB1,t+1,(t+4<NT),(t+2<NT),(t+2<NT));     ENDW(t+1); RESC(); ROT();
	ds_read_b64_tr_b16 v[102:103], v220 offset:32768
	ds_read_b64_tr_b16 v[104:105], v220 offset:33280
	v_add_f32_e32 v86, v130, v131
	v_add_f32_e32 v86, v132, v86
	v_add_f32_e32 v86, v133, v86
	v_add_f32_e32 v86, v134, v86
	v_add_f32_e32 v86, v135, v86
	v_cvt_pk_bf16_f32 v166, v130, v131
	v_cvt_pk_bf16_f32 v167, v132, v133
	s_waitcnt lgkmcnt(9)
	v_mfma_f32_32x32x16_bf16 v[114:129], v[82:85], v[174:177], v[50:65]
	ds_read_b64_tr_b16 v[130:131], v220 offset:36864
	ds_read_b64_tr_b16 v[132:133], v220 offset:37376
	v_add_f32_e32 v82, v136, v86
	v_add_f32_e32 v82, v137, v82
	v_add_f32_e32 v82, v138, v82
	v_add_f32_e32 v146, v139, v82
	v_cvt_pk_bf16_f32 v168, v134, v135
	v_cvt_pk_bf16_f32 v169, v136, v137
	s_waitcnt lgkmcnt(10)
	v_mfma_f32_32x32x16_bf16 v[82:97], v[106:109], v[174:177], v[50:65]
	ds_read_b64_tr_b16 v[106:107], v220 offset:33792
	ds_read_b64_tr_b16 v[108:109], v220 offset:34304
	s_waitcnt lgkmcnt(11)
	v_mfma_f32_32x32x16_bf16 v[114:129], v[110:113], v[170:173], v[114:129]
	v_add_f32_e32 v110, v140, v146
	v_add_f32_e32 v110, v141, v110
	v_add_f32_e32 v110, v142, v110
	v_add_f32_e32 v134, v143, v110
	v_cvt_pk_bf16_f32 v158, v138, v139
	v_cvt_pk_bf16_f32 v159, v140, v141
	ds_read_b64_tr_b16 v[110:111], v220 offset:37888
	ds_read_b64_tr_b16 v[112:113], v220 offset:38400
	v_add_f32_e32 v134, v144, v134
	v_add_f32_e32 v134, v145, v134
	v_add_f32_e32 v134, v66, v134
	v_add_f32_e32 v138, v67, v134
	v_cvt_pk_bf16_f32 v160, v142, v143
	v_cvt_pk_bf16_f32 v161, v144, v145
	s_waitcnt lgkmcnt(12)
	v_mfma_f32_32x32x16_bf16 v[82:97], v[178:181], v[170:173], v[82:97]
	ds_read_b64_tr_b16 v[134:135], v220 offset:34816
	ds_read_b64_tr_b16 v[136:137], v220 offset:35328
	v_add_f32_e32 v138, v68, v138
	v_add_f32_e32 v138, v69, v138
	v_add_f32_e32 v138, v70, v138
	v_add_f32_e32 v138, v71, v138
	v_cvt_pk_bf16_f32 v150, v66, v67
	v_cvt_pk_bf16_f32 v151, v68, v69
	s_waitcnt lgkmcnt(13)
	v_mfma_f32_32x32x16_bf16 v[114:129], v[182:185], v[162:165], v[114:129]
	ds_read_b64_tr_b16 v[66:67], v220 offset:38912
	ds_read_b64_tr_b16 v[68:69], v220 offset:39424
	v_add_f32_e32 v138, v72, v138
	v_add_f32_e32 v138, v73, v138
	v_add_f32_e32 v138, v74, v138
	v_add_f32_e32 v138, v75, v138
	v_cvt_pk_bf16_f32 v152, v70, v71
	v_cvt_pk_bf16_f32 v153, v72, v73
	s_waitcnt lgkmcnt(14)
	v_mfma_f32_32x32x16_bf16 v[82:97], v[186:189], v[162:165], v[82:97]
	ds_read_b64_tr_b16 v[70:71], v220 offset:35840
	ds_read_b64_tr_b16 v[72:73], v220 offset:36352
	v_add_f32_e32 v138, v76, v138
	v_add_f32_e32 v138, v77, v138
	v_add_f32_e32 v138, v78, v138
	v_add_f32_e32 v138, v79, v138
	v_cvt_pk_bf16_f32 v146, v74, v75
	v_cvt_pk_bf16_f32 v147, v76, v77
	s_waitcnt lgkmcnt(14)
	v_mfma_f32_32x32x16_bf16 v[114:129], v[212:215], v[154:157], v[114:129]
	ds_read_b64_tr_b16 v[74:75], v220 offset:39936
	ds_read_b64_tr_b16 v[76:77], v220 offset:40448
	v_mfma_f32_32x32x16_bf16 v[82:97], v[98:101], v[154:157], v[82:97]
	v_add_f32_e32 v98, v80, v138
	v_add_f32_e32 v98, v81, v98
	v_add_f32_e32 v98, 0, v98
	v_cvt_pk_bf16_f32 v148, v78, v79
	v_cvt_pk_bf16_f32 v149, v80, v81
	v_lshl_add_u64 v[78:79], v[210:211], 0, s[50:51]
	s_mov_b32 s12, m0
	s_mov_b32 m0, s4
	s_nop 0
	global_load_lds_dwordx4 v[78:79], off
	s_mov_b32 m0, s12
	v_add_f32_e32 v190, v190, v98
	s_waitcnt lgkmcnt(14)
	v_mfma_f32_32x32x16_bf16 v[18:33], v[166:169], v[102:105], v[18:33]
	v_exp_f32_e32 v114, v114
	v_exp_f32_e32 v115, v115
	v_exp_f32_e32 v116, v116
	v_exp_f32_e32 v117, v117
	s_waitcnt lgkmcnt(12)
	v_mfma_f32_32x32x16_bf16 v[34:49], v[166:169], v[130:133], v[34:49]
	v_exp_f32_e32 v118, v118
	v_exp_f32_e32 v119, v119
	v_exp_f32_e32 v120, v120
	v_exp_f32_e32 v121, v121
	ds_read_b128 v[78:81], v219
	ds_read_b128 v[138:141], v219 offset:512
	s_waitcnt lgkmcnt(12)
	v_mfma_f32_32x32x16_bf16 v[18:33], v[158:161], v[106:109], v[18:33]
	v_exp_f32_e32 v122, v122
	v_exp_f32_e32 v123, v123
	v_exp_f32_e32 v124, v124
	v_exp_f32_e32 v125, v125
	ds_read_b128 v[142:145], v219 offset:2048
	ds_read_b128 v[178:181], v219 offset:2560
	s_waitcnt lgkmcnt(12)
	v_mfma_f32_32x32x16_bf16 v[34:49], v[158:161], v[110:113], v[34:49]
	v_exp_f32_e32 v126, v126
	v_exp_f32_e32 v127, v127
	v_exp_f32_e32 v128, v128
	v_exp_f32_e32 v129, v129
	ds_read_b128 v[182:185], v219 offset:4096
	ds_read_b128 v[186:189], v219 offset:4608
	s_waitcnt lgkmcnt(12)
	v_mfma_f32_32x32x16_bf16 v[18:33], v[150:153], v[134:137], v[18:33]
	v_exp_f32_e32 v82, v82
	v_exp_f32_e32 v83, v83
	v_exp_f32_e32 v84, v84
	v_exp_f32_e32 v85, v85
	ds_read_b128 v[134:137], v219 offset:6144
	ds_read_b128 v[130:133], v219 offset:6656
	s_waitcnt lgkmcnt(12)
	v_mfma_f32_32x32x16_bf16 v[34:49], v[150:153], v[66:69], v[34:49]
	v_exp_f32_e32 v86, v86
	v_exp_f32_e32 v87, v87
	v_exp_f32_e32 v88, v88
	v_exp_f32_e32 v89, v89
	s_waitcnt lgkmcnt(10)
	v_mfma_f32_32x32x16_bf16 v[18:33], v[146:149], v[70:73], v[18:33]
	v_exp_f32_e32 v90, v90
	v_exp_f32_e32 v91, v91
	v_exp_f32_e32 v92, v92
	v_exp_f32_e32 v93, v93
	s_waitcnt lgkmcnt(8)
	v_mfma_f32_32x32x16_bf16 v[34:49], v[146:149], v[74:77], v[34:49]
	v_exp_f32_e32 v94, v94
	v_exp_f32_e32 v95, v95
	v_exp_f32_e32 v96, v96
	v_exp_f32_e32 v97, v97
	s_waitcnt vmcnt(1) lgkmcnt(0)
	s_barrier
; #define WAIT_BAR(N) asm volatile("s_waitcnt vmcnt(" #N ") lgkmcnt(0)\n\ts_barrier":::"memory")
;   #define RESC() do{}while(0)
;   #define ROT() do{sl_prev=sl_cur;sl_cur=sl_next;sl_next=(sl_next==(NSLOT-1)*SLOTB)?0:sl_next+SLOTB;}while(0)
;   #define ENDW(tt) do{ if((tt)+3<NT){WAIT_BAR(2);} else if((tt)+2<NT){WAIT_BAR(1);} else {WAIT_BAR(0);} }while(0)
; template<int THRL> __device__ __forceinline__ void attn_unit(int b,int h,int qb,const bf16*Q,const bf16*__restrict__ K,const bf16*__restrict__ V,bf16*O,char*shm,float m2){
;     ...
;   int t=1;
;   for(;t+5<NT;t+=2){
;     STEP(pB0,pB1,pA0,pA1,t,true,true,true);     WAIT_BAR(2); RESC(); ROT();
;     STEP(pA0,pA1,pB0,pB1,t+1,true,true,true);   WAIT_BAR(2); RESC(); ROT();
;   }
;     ...
;   for(;t+1<NT;t+=2){
;     STEP(pB0,pB1,pA0,pA1,t,(t+3<NT),(t+1<NT),(t+1<NT));       ENDW(t);   RESC(); ROT();
;     STEP(pA0,pA1,pB0,pB1,t+1,(t+4<NT),(t+2<NT),(t+2<NT));     ENDW(t+1); RESC(); ROT();
	ds_read_b64_tr_b16 v[212:213], v220 offset:40960
	ds_read_b64_tr_b16 v[214:215], v220 offset:41472
	v_add_f32_e32 v66, v114, v115
	v_add_f32_e32 v66, v116, v66
	v_add_f32_e32 v66, v117, v66
	v_add_f32_e32 v66, v118, v66
	v_add_f32_e32 v66, v119, v66
	v_cvt_pk_bf16_f32 v166, v114, v115
	v_cvt_pk_bf16_f32 v167, v116, v117
	s_waitcnt lgkmcnt(9)
	v_mfma_f32_32x32x16_bf16 v[98:113], v[78:81], v[174:177], v[50:65]
	ds_read_b64_tr_b16 v[114:115], v220 offset:45056
	ds_read_b64_tr_b16 v[116:117], v220 offset:45568
	v_add_f32_e32 v66, v120, v66
	v_add_f32_e32 v66, v121, v66
	v_add_f32_e32 v66, v122, v66
	v_add_f32_e32 v146, v123, v66
	s_waitcnt lgkmcnt(10)
	v_mfma_f32_32x32x16_bf16 v[66:81], v[138:141], v[174:177], v[50:65]
	v_cvt_pk_bf16_f32 v168, v118, v119
	v_cvt_pk_bf16_f32 v169, v120, v121
	ds_read_b64_tr_b16 v[138:139], v220 offset:41984
	ds_read_b64_tr_b16 v[140:141], v220 offset:42496
	v_add_f32_e32 v118, v124, v146
	v_add_f32_e32 v118, v125, v118
	v_add_f32_e32 v118, v126, v118
	v_add_f32_e32 v118, v127, v118
	v_cvt_pk_bf16_f32 v158, v122, v123
	v_cvt_pk_bf16_f32 v159, v124, v125
	s_waitcnt lgkmcnt(11)
	v_mfma_f32_32x32x16_bf16 v[98:113], v[142:145], v[170:173], v[98:113]
	ds_read_b64_tr_b16 v[120:121], v220 offset:46080
	ds_read_b64_tr_b16 v[122:123], v220 offset:46592
	s_waitcnt lgkmcnt(12)
	v_mfma_f32_32x32x16_bf16 v[66:81], v[178:181], v[170:173], v[66:81]
	v_add_f32_e32 v118, v128, v118
	v_add_f32_e32 v118, v129, v118
	v_add_f32_e32 v118, v82, v118
	v_add_f32_e32 v118, v83, v118
	v_cvt_pk_bf16_f32 v160, v126, v127
	v_cvt_pk_bf16_f32 v161, v128, v129
	ds_read_b64_tr_b16 v[124:125], v220 offset:43008
	ds_read_b64_tr_b16 v[126:127], v220 offset:43520
	v_add_f32_e32 v118, v84, v118
	v_add_f32_e32 v118, v85, v118
	v_add_f32_e32 v118, v86, v118
	v_add_f32_e32 v118, v87, v118
	v_cvt_pk_bf16_f32 v150, v82, v83
	v_cvt_pk_bf16_f32 v151, v84, v85
	s_waitcnt lgkmcnt(13)
	v_mfma_f32_32x32x16_bf16 v[98:113], v[182:185], v[162:165], v[98:113]
	ds_read_b64_tr_b16 v[82:83], v220 offset:47104
	ds_read_b64_tr_b16 v[84:85], v220 offset:47616
	s_waitcnt lgkmcnt(14)
	v_mfma_f32_32x32x16_bf16 v[66:81], v[186:189], v[162:165], v[66:81]
	v_add_f32_e32 v118, v88, v118
	v_add_f32_e32 v118, v89, v118
	v_add_f32_e32 v118, v90, v118
	v_add_f32_e32 v118, v91, v118
	v_cvt_pk_bf16_f32 v152, v86, v87
	v_cvt_pk_bf16_f32 v153, v88, v89
	ds_read_b64_tr_b16 v[86:87], v220 offset:44032
	ds_read_b64_tr_b16 v[88:89], v220 offset:44544
	v_add_f32_e32 v118, v92, v118
	v_add_f32_e32 v118, v93, v118
	v_add_f32_e32 v118, v94, v118
	v_add_f32_e32 v118, v95, v118
	v_cvt_pk_bf16_f32 v146, v90, v91
	v_cvt_pk_bf16_f32 v147, v92, v93
	s_waitcnt lgkmcnt(14)
	v_mfma_f32_32x32x16_bf16 v[98:113], v[134:137], v[154:157], v[98:113]
	ds_read_b64_tr_b16 v[90:91], v220 offset:48128
	ds_read_b64_tr_b16 v[92:93], v220 offset:48640
	v_mfma_f32_32x32x16_bf16 v[66:81], v[130:133], v[154:157], v[66:81]
	v_add_f32_e32 v118, v96, v118
	v_add_f32_e32 v118, v97, v118
	v_add_f32_e32 v118, 0, v118
	v_cvt_pk_bf16_f32 v148, v94, v95
	v_cvt_pk_bf16_f32 v149, v96, v97
	v_lshl_add_u64 v[94:95], v[210:211], 0, s[52:53]
	s_mov_b32 s4, m0
	s_mov_b32 m0, s5
	s_nop 0
	global_load_lds_dwordx4 v[94:95], off
	s_mov_b32 m0, s4
	v_add_f32_e32 v118, v190, v118
	s_waitcnt lgkmcnt(14)
	v_mfma_f32_32x32x16_bf16 v[18:33], v[166:169], v[212:215], v[18:33]
	v_exp_f32_e32 v98, v98
	v_exp_f32_e32 v99, v99
	v_exp_f32_e32 v100, v100
	v_exp_f32_e32 v101, v101
	s_waitcnt lgkmcnt(12)
	v_mfma_f32_32x32x16_bf16 v[34:49], v[166:169], v[114:117], v[34:49]
	v_exp_f32_e32 v102, v102
	v_exp_f32_e32 v103, v103
	v_exp_f32_e32 v104, v104
	v_exp_f32_e32 v105, v105
	ds_read_b128 v[128:131], v219 offset:8192
	ds_read_b128 v[132:135], v219 offset:8704
	s_waitcnt lgkmcnt(12)
	v_mfma_f32_32x32x16_bf16 v[18:33], v[158:161], v[138:141], v[18:33]
	v_exp_f32_e32 v106, v106
	v_exp_f32_e32 v107, v107
	v_exp_f32_e32 v108, v108
	v_exp_f32_e32 v109, v109
	ds_read_b128 v[136:139], v219 offset:10240
	ds_read_b128 v[140:143], v219 offset:10752
	s_waitcnt lgkmcnt(12)
	v_mfma_f32_32x32x16_bf16 v[34:49], v[158:161], v[120:123], v[34:49]
	v_exp_f32_e32 v110, v110
	v_exp_f32_e32 v111, v111
	v_exp_f32_e32 v112, v112
	v_exp_f32_e32 v113, v113
	ds_read_b128 v[120:123], v219 offset:12288
	ds_read_b128 v[178:181], v219 offset:12800
	s_waitcnt lgkmcnt(12)
	v_mfma_f32_32x32x16_bf16 v[18:33], v[150:153], v[124:127], v[18:33]
	v_exp_f32_e32 v66, v66
	v_exp_f32_e32 v67, v67
	v_exp_f32_e32 v68, v68
	v_exp_f32_e32 v69, v69
	ds_read_b128 v[124:127], v219 offset:14336
	ds_read_b128 v[114:117], v219 offset:14848
	s_waitcnt lgkmcnt(12)
	v_mfma_f32_32x32x16_bf16 v[34:49], v[150:153], v[82:85], v[34:49]
	v_exp_f32_e32 v70, v70
	v_exp_f32_e32 v71, v71
	v_exp_f32_e32 v72, v72
	v_exp_f32_e32 v73, v73
	s_waitcnt lgkmcnt(10)
	v_mfma_f32_32x32x16_bf16 v[18:33], v[146:149], v[86:89], v[18:33]
	v_exp_f32_e32 v74, v74
	v_exp_f32_e32 v75, v75
	v_exp_f32_e32 v76, v76
	v_exp_f32_e32 v77, v77
	s_waitcnt lgkmcnt(8)
	v_mfma_f32_32x32x16_bf16 v[34:49], v[146:149], v[90:93], v[34:49]
	v_exp_f32_e32 v78, v78
	v_exp_f32_e32 v79, v79
	v_exp_f32_e32 v80, v80
	v_exp_f32_e32 v81, v81
	s_waitcnt vmcnt(0) lgkmcnt(0)
	s_barrier
; #define WAIT_BAR(N) asm volatile("s_waitcnt vmcnt(" #N ") lgkmcnt(0)\n\ts_barrier":::"memory")
;   #define RESC() do{}while(0)
;   #define ROT() do{sl_prev=sl_cur;sl_cur=sl_next;sl_next=(sl_next==(NSLOT-1)*SLOTB)?0:sl_next+SLOTB;}while(0)
;   #define ENDW(tt) do{ if((tt)+3<NT){WAIT_BAR(2);} else if((tt)+2<NT){WAIT_BAR(1);} else {WAIT_BAR(0);} }while(0)
; template<int THRL> __device__ __forceinline__ void attn_unit(int b,int h,int qb,const bf16*Q,const bf16*__restrict__ K,const bf16*__restrict__ V,bf16*O,char*shm,float m2){
;     ...
;   int t=1;
;   for(;t+5<NT;t+=2){
;     STEP(pB0,pB1,pA0,pA1,t,true,true,true);     WAIT_BAR(2); RESC(); ROT();
;     STEP(pA0,pA1,pB0,pB1,t+1,true,true,true);   WAIT_BAR(2); RESC(); ROT();
;   }
;     ...
;   for(;t+1<NT;t+=2){
;     STEP(pB0,pB1,pA0,pA1,t,(t+3<NT),(t+1<NT),(t+1<NT));       ENDW(t);   RESC(); ROT();
;     STEP(pA0,pA1,pB0,pB1,t+1,(t+4<NT),(t+2<NT),(t+2<NT));     ENDW(t+1); RESC(); ROT();
;   }
;   STEP(pB0,pB1,pA0,pA1,NT-1,false,false,false); RESC();
	ds_read_b64_tr_b16 v[182:183], v220 offset:24576
	ds_read_b64_tr_b16 v[184:185], v220 offset:25088
	v_add_f32_e32 v82, v98, v99
	v_add_f32_e32 v82, v100, v82
	v_add_f32_e32 v82, v101, v82
	v_add_f32_e32 v82, v102, v82
	v_add_f32_e32 v119, v103, v82
	v_cvt_pk_bf16_f32 v166, v98, v99
	v_cvt_pk_bf16_f32 v167, v100, v101
	s_waitcnt lgkmcnt(9)
	v_mfma_f32_32x32x16_bf16 v[82:97], v[128:131], v[174:177], v[50:65]
	ds_read_b64_tr_b16 v[98:99], v220 offset:28672
	ds_read_b64_tr_b16 v[100:101], v220 offset:29184
	s_waitcnt lgkmcnt(10)
	v_mfma_f32_32x32x16_bf16 v[50:65], v[132:135], v[174:177], v[50:65]
	v_add_f32_e32 v119, v104, v119
	v_add_f32_e32 v119, v105, v119
	v_add_f32_e32 v119, v106, v119
	v_add_f32_e32 v119, v107, v119
	v_cvt_pk_bf16_f32 v168, v102, v103
	v_cvt_pk_bf16_f32 v169, v104, v105
	ds_read_b64_tr_b16 v[102:103], v220 offset:25600
	ds_read_b64_tr_b16 v[104:105], v220 offset:26112
	v_add_f32_e32 v119, v108, v119
	v_add_f32_e32 v119, v109, v119
	v_add_f32_e32 v119, v110, v119
	v_add_f32_e32 v119, v111, v119
	v_cvt_pk_bf16_f32 v158, v106, v107
	v_cvt_pk_bf16_f32 v159, v108, v109
	s_waitcnt lgkmcnt(11)
	v_mfma_f32_32x32x16_bf16 v[82:97], v[136:139], v[170:173], v[82:97]
	ds_read_b64_tr_b16 v[106:107], v220 offset:29696
	ds_read_b64_tr_b16 v[108:109], v220 offset:30208
	s_waitcnt lgkmcnt(12)
	v_mfma_f32_32x32x16_bf16 v[50:65], v[140:143], v[170:173], v[50:65]
	v_add_f32_e32 v119, v112, v119
	v_add_f32_e32 v119, v113, v119
	v_add_f32_e32 v119, v66, v119
	v_add_f32_e32 v119, v67, v119
	v_cvt_pk_bf16_f32 v160, v110, v111
	v_cvt_pk_bf16_f32 v161, v112, v113
	ds_read_b64_tr_b16 v[110:111], v220 offset:26624
	ds_read_b64_tr_b16 v[112:113], v220 offset:27136
	v_add_f32_e32 v119, v68, v119
	v_add_f32_e32 v119, v69, v119
	v_add_f32_e32 v119, v70, v119
	v_add_f32_e32 v119, v71, v119
	v_cvt_pk_bf16_f32 v150, v66, v67
	v_cvt_pk_bf16_f32 v151, v68, v69
	s_waitcnt lgkmcnt(13)
	v_mfma_f32_32x32x16_bf16 v[82:97], v[120:123], v[162:165], v[82:97]
	ds_read_b64_tr_b16 v[66:67], v220 offset:30720
	ds_read_b64_tr_b16 v[68:69], v220 offset:31232
	s_waitcnt lgkmcnt(14)
	v_mfma_f32_32x32x16_bf16 v[50:65], v[178:181], v[162:165], v[50:65]
	v_add_f32_e32 v119, v72, v119
	v_add_f32_e32 v119, v73, v119
	v_add_f32_e32 v119, v74, v119
	v_add_f32_e32 v119, v75, v119
	v_cvt_pk_bf16_f32 v152, v70, v71
	v_cvt_pk_bf16_f32 v153, v72, v73
	ds_read_b64_tr_b16 v[70:71], v220 offset:27648
	ds_read_b64_tr_b16 v[72:73], v220 offset:28160
	v_add_f32_e32 v119, v76, v119
	v_add_f32_e32 v119, v77, v119
	v_add_f32_e32 v119, v78, v119
	v_add_f32_e32 v119, v79, v119
	v_cvt_pk_bf16_f32 v146, v74, v75
	v_cvt_pk_bf16_f32 v147, v76, v77
	s_waitcnt lgkmcnt(14)
	v_mfma_f32_32x32x16_bf16 v[82:97], v[124:127], v[154:157], v[82:97]
	ds_read_b64_tr_b16 v[74:75], v220 offset:31744
	ds_read_b64_tr_b16 v[76:77], v220 offset:32256
	v_mfma_f32_32x32x16_bf16 v[50:65], v[114:117], v[154:157], v[50:65]
	v_add_f32_e32 v114, v80, v119
	v_add_f32_e32 v114, v81, v114
	v_add_f32_e32 v114, 0, v114
	v_cvt_pk_bf16_f32 v148, v78, v79
	v_cvt_pk_bf16_f32 v149, v80, v81
	s_waitcnt lgkmcnt(14)
	v_mfma_f32_32x32x16_bf16 v[18:33], v[166:169], v[182:185], v[18:33]
	s_nop 1
	v_exp_f32_e32 v82, v82
	v_exp_f32_e32 v83, v83
	v_exp_f32_e32 v84, v84
	v_exp_f32_e32 v85, v85
	s_waitcnt lgkmcnt(12)
	v_mfma_f32_32x32x16_bf16 v[34:49], v[166:169], v[98:101], v[34:49]
	v_exp_f32_e32 v86, v86
	v_exp_f32_e32 v87, v87
	v_exp_f32_e32 v88, v88
	v_exp_f32_e32 v89, v89
	s_waitcnt lgkmcnt(10)
	v_mfma_f32_32x32x16_bf16 v[18:33], v[158:161], v[102:105], v[18:33]
	v_exp_f32_e32 v90, v90
	v_exp_f32_e32 v91, v91
	v_exp_f32_e32 v92, v92
	v_exp_f32_e32 v93, v93
	s_waitcnt lgkmcnt(8)
	v_mfma_f32_32x32x16_bf16 v[34:49], v[158:161], v[106:109], v[34:49]
	v_exp_f32_e32 v94, v94
	v_exp_f32_e32 v95, v95
	v_exp_f32_e32 v96, v96
	v_exp_f32_e32 v97, v97
	s_waitcnt lgkmcnt(6)
; #define SBAR() __builtin_amdgcn_sched_barrier(0)
;   #define RESC() do{}while(0)
;   #define PKW(P,B) cvtpk_s(P[B],P[B+1])
; __device__ __forceinline__ void pv(f32x16*o,int vb,bf16x8 pa0,bf16x8 pa1,bf16x8 pa2,bf16x8 pa3){
;   #pragma unroll
;   for(int d0=0;d0<2;++d0){s16x4 lo[4],hi[4];
;     #pragma unroll
;     for(int ks=0;ks<4;++ks){
;       asm volatile("ds_read_b64_tr_b16 %0,%1 offset:%c2":"=&v"(lo[ks]):"v"(vb),"i"(d0*4096+ks*1024):"memory");
;       asm volatile("ds_read_b64_tr_b16 %0,%1 offset:%c2":"=&v"(hi[ks]):"v"(vb),"i"(d0*4096+ks*1024+512):"memory");}
;     asm volatile("s_waitcnt lgkmcnt(0)":::"memory");SBAR();
;     ...
;     o[d0]=__builtin_amdgcn_mfma_f32_32x32x16_bf16(pa0,PK(0),o[d0],0,0,0);
;     o[d0]=__builtin_amdgcn_mfma_f32_32x32x16_bf16(pa1,PK(1),o[d0],0,0,0);
;     o[d0]=__builtin_amdgcn_mfma_f32_32x32x16_bf16(pa2,PK(2),o[d0],0,0,0);
;     o[d0]=__builtin_amdgcn_mfma_f32_32x32x16_bf16(pa3,PK(3),o[d0],0,0,0);
;     ...
;   }
; }
; template<int THRL> __device__ __forceinline__ void attn_unit(int b,int h,int qb,const bf16*Q,const bf16*__restrict__ K,const bf16*__restrict__ V,bf16*O,char*shm,float m2){
;     ...
;   STEP(pB0,pB1,pA0,pA1,NT-1,false,false,false); RESC();
;   { float sacc=pB0[0]+pB0[1]; _Pragma("unroll") for(int r=2;r<16;++r)sacc+=pB0[r]; _Pragma("unroll") for(int r=0;r<16;++r)sacc+=pB1[r]; l_reg+=sacc;
;     pw0=(u32x4){PKW(pB0,0),PKW(pB0,2),PKW(pB0,4),PKW(pB0,6)};pw1=(u32x4){PKW(pB0,8),PKW(pB0,10),PKW(pB0,12),PKW(pB0,14)};pw2=(u32x4){PKW(pB1,0),PKW(pB1,2),PKW(pB1,4),PKW(pB1,6)};pw3=(u32x4){PKW(pB1,8),PKW(pB1,10),PKW(pB1,12),PKW(pB1,14)};
;     SBAR(); pv(o,vb0+sl_cur,PAF(0),PAF(1),PAF(2),PAF(3)); }
;     ...
;   {auto rr=__builtin_amdgcn_permlane32_swap(__float_as_uint(l_reg),__float_as_uint(l_reg),false,false);l_reg=__uint_as_float(rr[0])+__uint_as_float(rr[1]);}
;   if(hi==0)wsf[32+r32]=l_reg;asm volatile("s_waitcnt lgkmcnt(0)":::"memory");
	v_mfma_f32_32x32x16_bf16 v[18:33], v[150:153], v[110:113], v[18:33]
	v_exp_f32_e32 v50, v50
	v_exp_f32_e32 v51, v51
	v_exp_f32_e32 v52, v52
	v_exp_f32_e32 v53, v53
	s_waitcnt lgkmcnt(4)
	v_mfma_f32_32x32x16_bf16 v[34:49], v[150:153], v[66:69], v[34:49]
	v_exp_f32_e32 v54, v54
	v_exp_f32_e32 v55, v55
	v_exp_f32_e32 v56, v56
	v_exp_f32_e32 v57, v57
	s_waitcnt lgkmcnt(2)
	v_mfma_f32_32x32x16_bf16 v[18:33], v[146:149], v[70:73], v[18:33]
	v_exp_f32_e32 v58, v58
	v_exp_f32_e32 v59, v59
	v_exp_f32_e32 v60, v60
	v_exp_f32_e32 v61, v61
	s_waitcnt lgkmcnt(0)
	v_mfma_f32_32x32x16_bf16 v[34:49], v[146:149], v[74:77], v[34:49]
	v_exp_f32_e32 v62, v62
	v_exp_f32_e32 v63, v63
	v_exp_f32_e32 v64, v64
	v_exp_f32_e32 v65, v65
	v_add_f32_e32 v66, v82, v83
	v_add_f32_e32 v66, v84, v66
	v_add_f32_e32 v66, v85, v66
	v_add_f32_e32 v66, v86, v66
	v_add_f32_e32 v66, v87, v66
	v_add_f32_e32 v66, v88, v66
	v_add_f32_e32 v66, v89, v66
	v_add_f32_e32 v66, v90, v66
	v_add_f32_e32 v66, v91, v66
	v_add_f32_e32 v66, v92, v66
	v_add_f32_e32 v66, v93, v66
	v_add_f32_e32 v66, v94, v66
	v_add_f32_e32 v66, v95, v66
	v_add_f32_e32 v66, v96, v66
	v_add_f32_e32 v66, v97, v66
	v_add_f32_e32 v66, v50, v66
	v_add_f32_e32 v66, v51, v66
	v_add_f32_e32 v66, v52, v66
	v_add_f32_e32 v66, v53, v66
	v_add_f32_e32 v66, v54, v66
	v_add_f32_e32 v66, v55, v66
	v_add_f32_e32 v66, v56, v66
	v_add_f32_e32 v66, v57, v66
	v_add_f32_e32 v66, v58, v66
	v_add_f32_e32 v66, v59, v66
	v_add_f32_e32 v66, v60, v66
	v_add_f32_e32 v66, v61, v66
	v_add_f32_e32 v66, v62, v66
	v_add_f32_e32 v66, v63, v66
	v_add_f32_e32 v66, v64, v66
	v_add_f32_e32 v66, v65, v66
	v_add_f32_e32 v67, v118, v114
	v_add_f32_e32 v66, v67, v66
	v_cvt_pk_bf16_f32 v50, v50, v51
	v_cvt_pk_bf16_f32 v68, v82, v83
	v_cvt_pk_bf16_f32 v69, v84, v85
	v_cvt_pk_bf16_f32 v70, v86, v87
	v_cvt_pk_bf16_f32 v71, v88, v89
	v_cvt_pk_bf16_f32 v72, v90, v91
	v_cvt_pk_bf16_f32 v73, v92, v93
	v_cvt_pk_bf16_f32 v74, v94, v95
	v_cvt_pk_bf16_f32 v75, v96, v97
	v_cvt_pk_bf16_f32 v51, v52, v53
	v_cvt_pk_bf16_f32 v52, v54, v55
	v_cvt_pk_bf16_f32 v53, v56, v57
	v_cvt_pk_bf16_f32 v54, v58, v59
	v_cvt_pk_bf16_f32 v55, v60, v61
	v_cvt_pk_bf16_f32 v56, v62, v63
	v_cvt_pk_bf16_f32 v57, v64, v65
	ds_read_b64_tr_b16 v[58:59],v221 offset:0
	ds_read_b64_tr_b16 v[60:61],v221 offset:512
	ds_read_b64_tr_b16 v[62:63],v221 offset:1024
	ds_read_b64_tr_b16 v[64:65],v221 offset:1536
	ds_read_b64_tr_b16 v[76:77],v221 offset:2048
	ds_read_b64_tr_b16 v[78:79],v221 offset:2560
	ds_read_b64_tr_b16 v[80:81],v221 offset:3072
	ds_read_b64_tr_b16 v[82:83],v221 offset:3584
	s_waitcnt lgkmcnt(0)
	s_nop 0
	v_mfma_f32_32x32x16_bf16 v[18:33], v[68:71], v[58:61], v[18:33]
	ds_read_b64_tr_b16 v[58:59],v221 offset:4096
	ds_read_b64_tr_b16 v[60:61],v221 offset:4608
	v_mfma_f32_32x32x16_bf16 v[18:33], v[72:75], v[62:65], v[18:33]
	ds_read_b64_tr_b16 v[62:63],v221 offset:5120
	ds_read_b64_tr_b16 v[64:65],v221 offset:5632
	v_mfma_f32_32x32x16_bf16 v[18:33], v[50:53], v[76:79], v[18:33]
	ds_read_b64_tr_b16 v[76:77],v221 offset:6144
	ds_read_b64_tr_b16 v[78:79],v221 offset:6656
	v_mfma_f32_32x32x16_bf16 v[18:33], v[54:57], v[80:83], v[18:33]
	ds_read_b64_tr_b16 v[80:81],v221 offset:7168
	ds_read_b64_tr_b16 v[82:83],v221 offset:7680
	s_waitcnt lgkmcnt(0)
	v_mfma_f32_32x32x16_bf16 v[34:49], v[68:71], v[58:61], v[34:49]
	v_mfma_f32_32x32x16_bf16 v[34:49], v[72:75], v[62:65], v[34:49]
	v_mfma_f32_32x32x16_bf16 v[34:49], v[50:53], v[76:79], v[34:49]
	v_mov_b32_e32 v50, v66
	s_nop 1
	v_permlane32_swap_b32_e32 v66, v50
	v_mfma_f32_32x32x16_bf16 v[34:49], v[54:57], v[80:83], v[34:49]
	s_and_saveexec_b64 s[4:5], s[2:3]
	s_cbranch_execz .LBB0_823
	v_add_f32_e32 v50, v66, v50
	v_lshl_add_u32 v51, v1, 2, s0
	ds_write_b32 v51, v50 offset:49280
	s_branch .LBB0_823
